# v13 + cache K/V conversion loops (prologue_b) software-pipelined: next item's loads issued before current item's stores
# baseline (speedup 1.0000x reference)
; DI void kc_item(const float* src, int past, int nh, int band, int krows, bf16_t* KF, int item, int lane) {
;     const int nrb = past / 32, h = item % nh, rb = (item / nh) % nrb, b = item / (nh * nrb), r = lane & 31, hh = lane >> 5;
;     const float* sp = src + (((size_t)b * past + rb * 32 + r) * nh + h) * 64 + 8 * hh;
;     bf16_t* d = KF + (((size_t)h * (krows >> 5) + ((SEQ + b * band) >> 5) + rb) * 4 * 64 + lane) * 8;
; #pragma unroll
;     for (int ds = 0; ds < 4; ++ds) { const f32x4 v0 = *(const f32x4*)(sp + 16 * ds), v1 = *(const f32x4*)(sp + 16 * ds + 4);
;         u32x4 o; o.x = pk2(v0[0], v0[1]); o.y = pk2(v0[2], v0[3]); o.z = pk2(v1[0], v1[1]); o.w = pk2(v1[2], v1[3]);
;         *(u32x4*)(d + ds * 512) = o; }
; }
; DI void prologue_b(KArgs ap, int gw, int NGW, int lane) {
;     ...
;     for (int it = gw; it < NSTREAM * 16 * 8; it += NGW) kc_item(cak, 512, 8, 576, KA_ROWS, (bf16_t*)(ws + WS_KA), it, lane);
.LBB0_537:
	s_ashr_i32 s11, s10, 31
	s_lshr_b32 s18, s11, 29
	s_lshr_b32 s11, s11, 25
	s_add_i32 s18, s10, s18
	s_add_i32 s11, s10, s11
	s_ashr_i32 s26, s18, 3
	s_and_b32 s19, s18, -8
	s_ashr_i32 s18, s11, 7
	s_lshr_b32 s11, s26, 28
	s_add_i32 s11, s26, s11
	s_and_b32 s11, s11, -16
	s_sub_i32 s20, s10, s19
	s_ashr_i32 s19, s18, 31
	s_sub_i32 s11, s26, s11
	s_ashr_i32 s21, s20, 31
	s_lshl_b64 s[22:23], s[18:19], 20
	s_lshl_b32 s19, s11, 5
	s_lshl_b64 s[24:25], s[20:21], 8
	s_ashr_i32 s21, s19, 31
	v_or_b32_e32 v6, s19, v0
	v_mov_b32_e32 v7, s21
	v_lshlrev_b64 v[6:7], 11, v[6:7]
	v_lshl_add_u64 v[6:7], v[2:3], 0, v[6:7]
	v_lshl_add_u64 v[6:7], v[6:7], 0, s[22:23]
	v_lshl_add_u64 v[14:15], v[6:7], 0, s[24:25]
	global_load_dwordx4 v[68:71], v[14:15], off
	global_load_dwordx4 v[72:75], v[14:15], off offset:16
	global_load_dwordx4 v[76:79], v[14:15], off offset:64
	global_load_dwordx4 v[80:83], v[14:15], off offset:80
	global_load_dwordx4 v[84:87], v[14:15], off offset:128
	global_load_dwordx4 v[88:91], v[14:15], off offset:144
	global_load_dwordx4 v[92:95], v[14:15], off offset:192
	global_load_dwordx4 v[96:99], v[14:15], off offset:208
	s_mulk_i32 s18, 0x240
	s_addk_i32 s18, 0x4000
	s_ashr_i32 s18, s18, 5
	s_mul_hi_i32 s19, s20, 0x440
	s_mulk_i32 s20, 0x440
	s_ashr_i32 s21, s18, 31
	s_ashr_i32 s22, s11, 31
	s_add_u32 s11, s20, s11
	s_addc_u32 s19, s19, s22
	s_add_u32 s18, s11, s18
	s_addc_u32 s19, s19, s21
	s_lshl_b64 s[18:19], s[18:19], 12
	v_lshl_add_u64 v[16:17], v[4:5], 0, s[18:19]
	s_add_i32 s10, s10, s17
	s_cmpk_gt_i32 s10, 0xfff
	s_cselect_b32 s45, 0, 1
	s_waitcnt vmcnt(0)
	s_branch .Lkc_entry
.Lkc_top:
	s_waitcnt vmcnt(4)
.Lkc_entry:
	v_cvt_pk_bf16_f32 v104, v68, v69
	v_cvt_pk_bf16_f32 v105, v70, v71
	v_cvt_pk_bf16_f32 v106, v72, v73
	v_cvt_pk_bf16_f32 v107, v74, v75
	v_cvt_pk_bf16_f32 v108, v76, v77
	v_cvt_pk_bf16_f32 v109, v78, v79
	v_cvt_pk_bf16_f32 v110, v80, v81
	v_cvt_pk_bf16_f32 v111, v82, v83
	v_cvt_pk_bf16_f32 v112, v84, v85
	v_cvt_pk_bf16_f32 v113, v86, v87
	v_cvt_pk_bf16_f32 v114, v88, v89
	v_cvt_pk_bf16_f32 v115, v90, v91
	v_cvt_pk_bf16_f32 v116, v92, v93
	v_cvt_pk_bf16_f32 v117, v94, v95
	v_cvt_pk_bf16_f32 v118, v96, v97
	v_cvt_pk_bf16_f32 v119, v98, v99
	v_mov_b64_e32 v[100:101], v[16:17]
	s_mov_b32 s46, s45
	s_cmp_lg_u32 s45, 0
	s_cbranch_scc0 .Lkc_nold
	s_ashr_i32 s11, s10, 31
	s_lshr_b32 s18, s11, 29
	s_lshr_b32 s11, s11, 25
	s_add_i32 s18, s10, s18
	s_add_i32 s11, s10, s11
	s_ashr_i32 s26, s18, 3
	s_and_b32 s19, s18, -8
	s_ashr_i32 s18, s11, 7
	s_lshr_b32 s11, s26, 28
	s_add_i32 s11, s26, s11
	s_and_b32 s11, s11, -16
	s_sub_i32 s20, s10, s19
	s_ashr_i32 s19, s18, 31
	s_sub_i32 s11, s26, s11
	s_ashr_i32 s21, s20, 31
	s_lshl_b64 s[22:23], s[18:19], 20
	s_lshl_b32 s19, s11, 5
	s_lshl_b64 s[24:25], s[20:21], 8
	s_ashr_i32 s21, s19, 31
	v_or_b32_e32 v6, s19, v0
	v_mov_b32_e32 v7, s21
	v_lshlrev_b64 v[6:7], 11, v[6:7]
	v_lshl_add_u64 v[6:7], v[2:3], 0, v[6:7]
	v_lshl_add_u64 v[6:7], v[6:7], 0, s[22:23]
	v_lshl_add_u64 v[14:15], v[6:7], 0, s[24:25]
	global_load_dwordx4 v[68:71], v[14:15], off
	global_load_dwordx4 v[72:75], v[14:15], off offset:16
	global_load_dwordx4 v[76:79], v[14:15], off offset:64
	global_load_dwordx4 v[80:83], v[14:15], off offset:80
	global_load_dwordx4 v[84:87], v[14:15], off offset:128
	global_load_dwordx4 v[88:91], v[14:15], off offset:144
	global_load_dwordx4 v[92:95], v[14:15], off offset:192
	global_load_dwordx4 v[96:99], v[14:15], off offset:208
	s_mulk_i32 s18, 0x240
	s_addk_i32 s18, 0x4000
	s_ashr_i32 s18, s18, 5
	s_mul_hi_i32 s19, s20, 0x440
	s_mulk_i32 s20, 0x440
	s_ashr_i32 s21, s18, 31
	s_ashr_i32 s22, s11, 31
	s_add_u32 s11, s20, s11
	s_addc_u32 s19, s19, s22
	s_add_u32 s18, s11, s18
	s_addc_u32 s19, s19, s21
	s_lshl_b64 s[18:19], s[18:19], 12
	v_lshl_add_u64 v[16:17], v[4:5], 0, s[18:19]
	s_add_i32 s10, s10, s17
	s_cmpk_gt_i32 s10, 0xfff
	s_cselect_b32 s45, 0, 1
.Lkc_nold:
	global_store_dwordx4 v[100:101], v[104:107], off
	global_store_dwordx4 v[100:101], v[108:111], off offset:1024
	global_store_dwordx4 v[100:101], v[112:115], off offset:2048
	global_store_dwordx4 v[100:101], v[116:119], off offset:3072
	s_cmp_lg_u32 s46, 0
	s_cbranch_scc1 .Lkc_top

; DI size_t vf_off(int h, int nblk, int krow, int d) { const int kk = krow & 31; return (((((size_t)h * nblk + (krow >> 5)) * 2 + (d >> 5)) * 2 + (kk >> 4)) * 64 + ((kk >> 2) & 1) * 32 + (d & 31)) * 8 + 4 * ((kk >> 3) & 1) + (kk & 3); }
; DI void vt_item(const float* src, int past, int nh, int band, int krows, bf16_t* VT, int item, int lane) {
;     const int nrb = past / 32, rb = item % nrb, h = (item / nrb) % nh, b = item / (nrb * nh), r0 = rb * 32;
;     float v[32];
; #pragma unroll
;     for (int i = 0; i < 32; ++i) v[i] = src[(((size_t)b * past + r0 + i) * nh + h) * 64 + lane];
;     const int krow = SEQ + b * band + r0;
; #pragma unroll
;     for (int t = 0; t < 2; ++t)
; #pragma unroll
;         for (int hh = 0; hh < 2; ++hh) { const int k0 = 16 * t + 4 * hh; u32x4 o; o.x = pk2(v[k0], v[k0 + 1]); o.y = pk2(v[k0 + 2], v[k0 + 3]); o.z = pk2(v[k0 + 8], v[k0 + 9]); o.w = pk2(v[k0 + 10], v[k0 + 11]);
;             *(u32x4*)(VT + vf_off(h, krows >> 5, krow + k0, lane)) = o; }
; }
; DI void prologue_b(KArgs ap, int gw, int NGW, int lane) {
;     ...
;     for (int it = gw; it < NSTREAM * 8 * 16; it += NGW) vt_item(cav, 512, 8, 576, KA_ROWS, (bf16_t*)(ws + WS_VTA), it, lane);
.LBB0_543:
	s_ashr_i32 s4, s34, 31
	s_lshr_b32 s5, s4, 28
	s_lshr_b32 s4, s4, 25
	s_add_i32 s5, s34, s5
	s_add_i32 s4, s34, s4
	s_ashr_i32 s35, s5, 4
	s_ashr_i32 s4, s4, 7
	s_lshr_b32 s6, s35, 29
	s_lshl_b32 s44, s35, 9
	s_ashr_i32 s5, s4, 31
	s_add_i32 s43, s35, s6
	s_sub_i32 s42, s12, s44
	s_lshl_b64 s[6:7], s[4:5], 20
	s_and_b32 s5, s43, -8
	s_ashr_i32 s43, s42, 31
	v_lshl_add_u64 v[6:7], v[2:3], 0, s[6:7]
	s_sub_i32 s6, s35, s5
	s_lshl_b64 s[42:43], s[42:43], 11
	s_ashr_i32 s7, s6, 31
	v_lshl_add_u64 v[6:7], v[6:7], 0, s[42:43]
	s_lshl_b64 s[42:43], s[6:7], 8
	v_lshl_add_u64 v[6:7], v[6:7], 0, s[42:43]
	v_add_co_u32_e32 v8, vcc, s18, v6
	global_load_dword v154, v[6:7], off
	global_load_dword v155, v[6:7], off offset:2048
	v_addc_co_u32_e32 v9, vcc, 0, v7, vcc
	v_add_co_u32_e32 v10, vcc, s19, v6
	s_mulk_i32 s4, 0x240
	s_nop 0
	v_addc_co_u32_e32 v11, vcc, 0, v7, vcc
	v_add_co_u32_e32 v12, vcc, s20, v6
	s_sub_i32 s4, s4, s44
	s_nop 0
	v_addc_co_u32_e32 v13, vcc, 0, v7, vcc
	v_add_co_u32_e32 v14, vcc, s21, v6
	s_add_i32 s4, s12, s4
	s_nop 0
	v_addc_co_u32_e32 v15, vcc, 0, v7, vcc
	v_add_co_u32_e32 v16, vcc, s22, v6
	s_addk_i32 s4, 0x4000
	s_nop 0
	v_addc_co_u32_e32 v17, vcc, 0, v7, vcc
	v_add_co_u32_e32 v18, vcc, s23, v6
	s_ashr_i32 s4, s4, 5
	s_nop 0
	v_addc_co_u32_e32 v19, vcc, 0, v7, vcc
	v_add_co_u32_e32 v20, vcc, s24, v6
	s_mul_hi_i32 s5, s6, 0x440
	s_nop 0
	v_addc_co_u32_e32 v21, vcc, 0, v7, vcc
	v_add_co_u32_e32 v22, vcc, s25, v6
	s_mulk_i32 s6, 0x440
	s_nop 0
	v_addc_co_u32_e32 v23, vcc, 0, v7, vcc
	v_add_co_u32_e32 v24, vcc, s26, v6
	s_ashr_i32 s7, s4, 31
	s_nop 0
	v_addc_co_u32_e32 v25, vcc, 0, v7, vcc
	v_add_co_u32_e32 v26, vcc, s27, v6
	s_add_u32 s4, s6, s4
	s_nop 0
	v_addc_co_u32_e32 v27, vcc, 0, v7, vcc
	v_add_co_u32_e32 v28, vcc, s28, v6
	s_addc_u32 s5, s5, s7
	s_nop 0
	v_addc_co_u32_e32 v29, vcc, 0, v7, vcc
	v_add_co_u32_e32 v30, vcc, s29, v6
	s_add_i32 s34, s34, s17
	s_nop 0
	v_addc_co_u32_e32 v31, vcc, 0, v7, vcc
	v_add_co_u32_e32 v32, vcc, s30, v6
	s_add_i32 s12, s12, s13
	s_nop 0
	v_addc_co_u32_e32 v33, vcc, 0, v7, vcc
	v_add_co_u32_e32 v34, vcc, s31, v6
	s_lshl_b64 s[4:5], s[4:5], 12
	s_nop 0
	v_addc_co_u32_e32 v35, vcc, 0, v7, vcc
	v_add_co_u32_e32 v6, vcc, s33, v6
	s_cmpk_gt_i32 s34, 0xfff
	s_nop 0
	v_addc_co_u32_e32 v7, vcc, 0, v7, vcc
	global_load_dword v156, v[14:15], off offset:2048
	global_load_dword v157, v[18:19], off offset:-4096
	global_load_dword v158, v[18:19], off
	global_load_dword v159, v[18:19], off offset:2048
	global_load_dword v160, v[22:23], off offset:-4096
	global_load_dword v161, v[22:23], off
	global_load_dword v162, v[22:23], off offset:2048
	global_load_dword v163, v[26:27], off offset:-4096
	global_load_dword v164, v[8:9], off offset:2048
	global_load_dword v165, v[12:13], off offset:2048
	global_load_dword v166, v[16:17], off offset:2048
	global_load_dword v167, v[20:21], off offset:2048
	global_load_dword v168, v[24:25], off offset:2048
	global_load_dword v169, v[28:29], off offset:2048
	global_load_dword v170, v[10:11], off offset:-4096
	global_load_dword v171, v[10:11], off
	global_load_dword v172, v[14:15], off
	global_load_dword v173, v[10:11], off offset:2048
	global_load_dword v174, v[14:15], off offset:-4096
	global_load_dword v175, v[32:33], off offset:2048
	global_load_dword v176, v[26:27], off
	global_load_dword v177, v[26:27], off offset:2048
	global_load_dword v178, v[30:31], off offset:-4096
	global_load_dword v179, v[30:31], off
	global_load_dword v180, v[30:31], off offset:2048
	global_load_dword v181, v[34:35], off offset:-4096
	global_load_dword v182, v[34:35], off
	global_load_dword v183, v[34:35], off offset:2048
	global_load_dword v184, v[6:7], off
	global_load_dword v185, v[6:7], off offset:2048
	v_lshl_add_u64 v[22:23], v[4:5], 0, s[4:5]
	s_cselect_b32 s47, 0, 1
	s_waitcnt vmcnt(0)
	s_branch .Lvt_entry

; DI size_t vf_off(int h, int nblk, int krow, int d) { const int kk = krow & 31; return (((((size_t)h * nblk + (krow >> 5)) * 2 + (d >> 5)) * 2 + (kk >> 4)) * 64 + ((kk >> 2) & 1) * 32 + (d & 31)) * 8 + 4 * ((kk >> 3) & 1) + (kk & 3); }
; DI void vt_item(const float* src, int past, int nh, int band, int krows, bf16_t* VT, int item, int lane) {
;     const int nrb = past / 32, rb = item % nrb, h = (item / nrb) % nh, b = item / (nrb * nh), r0 = rb * 32;
;     float v[32];
; #pragma unroll
;     for (int i = 0; i < 32; ++i) v[i] = src[(((size_t)b * past + r0 + i) * nh + h) * 64 + lane];
;     const int krow = SEQ + b * band + r0;
; #pragma unroll
;     for (int t = 0; t < 2; ++t)
; #pragma unroll
;         for (int hh = 0; hh < 2; ++hh) { const int k0 = 16 * t + 4 * hh; u32x4 o; o.x = pk2(v[k0], v[k0 + 1]); o.y = pk2(v[k0 + 2], v[k0 + 3]); o.z = pk2(v[k0 + 8], v[k0 + 9]); o.w = pk2(v[k0 + 10], v[k0 + 11]);
;             *(u32x4*)(VT + vf_off(h, krows >> 5, krow + k0, lane)) = o; }
; }
.Lvt_entry:
	v_cvt_pk_bf16_f32 v104, v154, v155
	v_cvt_pk_bf16_f32 v112, v161, v162
	v_cvt_pk_bf16_f32 v107, v157, v166
	v_cvt_pk_bf16_f32 v113, v163, v168
	v_cvt_pk_bf16_f32 v105, v170, v164
	v_cvt_pk_bf16_f32 v106, v172, v156
	v_cvt_pk_bf16_f32 v108, v171, v173
	v_cvt_pk_bf16_f32 v109, v174, v165
	v_cvt_pk_bf16_f32 v110, v158, v159
	v_cvt_pk_bf16_f32 v111, v160, v167
	v_cvt_pk_bf16_f32 v116, v176, v177
	v_cvt_pk_bf16_f32 v117, v178, v169
	v_cvt_pk_bf16_f32 v114, v179, v180
	v_cvt_pk_bf16_f32 v115, v181, v175
	v_cvt_pk_bf16_f32 v118, v182, v183
	v_cvt_pk_bf16_f32 v119, v184, v185
	v_mov_b64_e32 v[186:187], v[22:23]
	s_mov_b32 s48, s47
	s_cmp_lg_u32 s47, 0
	s_cbranch_scc0 .Lvt_nold
	s_ashr_i32 s4, s34, 31
	s_lshr_b32 s5, s4, 28
	s_lshr_b32 s4, s4, 25
	s_add_i32 s5, s34, s5
	s_add_i32 s4, s34, s4
	s_ashr_i32 s35, s5, 4
	s_ashr_i32 s4, s4, 7
	s_lshr_b32 s6, s35, 29
	s_lshl_b32 s44, s35, 9
	s_ashr_i32 s5, s4, 31
	s_add_i32 s43, s35, s6
	s_sub_i32 s42, s12, s44
	s_lshl_b64 s[6:7], s[4:5], 20
	s_and_b32 s5, s43, -8
	s_ashr_i32 s43, s42, 31
	v_lshl_add_u64 v[6:7], v[2:3], 0, s[6:7]
	s_sub_i32 s6, s35, s5
	s_lshl_b64 s[42:43], s[42:43], 11
	s_ashr_i32 s7, s6, 31
	v_lshl_add_u64 v[6:7], v[6:7], 0, s[42:43]
	s_lshl_b64 s[42:43], s[6:7], 8
	v_lshl_add_u64 v[6:7], v[6:7], 0, s[42:43]
	v_add_co_u32_e32 v8, vcc, s18, v6
	global_load_dword v154, v[6:7], off
	global_load_dword v155, v[6:7], off offset:2048
	v_addc_co_u32_e32 v9, vcc, 0, v7, vcc
	v_add_co_u32_e32 v10, vcc, s19, v6
	s_mulk_i32 s4, 0x240
	s_nop 0
	v_addc_co_u32_e32 v11, vcc, 0, v7, vcc
	v_add_co_u32_e32 v12, vcc, s20, v6
	s_sub_i32 s4, s4, s44
	s_nop 0
	v_addc_co_u32_e32 v13, vcc, 0, v7, vcc
	v_add_co_u32_e32 v14, vcc, s21, v6
	s_add_i32 s4, s12, s4
	s_nop 0
	v_addc_co_u32_e32 v15, vcc, 0, v7, vcc
	v_add_co_u32_e32 v16, vcc, s22, v6
	s_addk_i32 s4, 0x4000
	s_nop 0
	v_addc_co_u32_e32 v17, vcc, 0, v7, vcc
	v_add_co_u32_e32 v18, vcc, s23, v6
	s_ashr_i32 s4, s4, 5
	s_nop 0
	v_addc_co_u32_e32 v19, vcc, 0, v7, vcc
	v_add_co_u32_e32 v20, vcc, s24, v6
	s_mul_hi_i32 s5, s6, 0x440
	s_nop 0
	v_addc_co_u32_e32 v21, vcc, 0, v7, vcc
	v_add_co_u32_e32 v22, vcc, s25, v6
	s_mulk_i32 s6, 0x440
	s_nop 0
	v_addc_co_u32_e32 v23, vcc, 0, v7, vcc
	v_add_co_u32_e32 v24, vcc, s26, v6
	s_ashr_i32 s7, s4, 31
	s_nop 0
	v_addc_co_u32_e32 v25, vcc, 0, v7, vcc
	v_add_co_u32_e32 v26, vcc, s27, v6
	s_add_u32 s4, s6, s4
	s_nop 0
	v_addc_co_u32_e32 v27, vcc, 0, v7, vcc
	v_add_co_u32_e32 v28, vcc, s28, v6
	s_addc_u32 s5, s5, s7
	s_nop 0
	v_addc_co_u32_e32 v29, vcc, 0, v7, vcc
	v_add_co_u32_e32 v30, vcc, s29, v6
	s_add_i32 s34, s34, s17
	s_nop 0
	v_addc_co_u32_e32 v31, vcc, 0, v7, vcc
	v_add_co_u32_e32 v32, vcc, s30, v6
	s_add_i32 s12, s12, s13
	s_nop 0
	v_addc_co_u32_e32 v33, vcc, 0, v7, vcc
	v_add_co_u32_e32 v34, vcc, s31, v6
	s_lshl_b64 s[4:5], s[4:5], 12
	s_nop 0
	v_addc_co_u32_e32 v35, vcc, 0, v7, vcc
	v_add_co_u32_e32 v6, vcc, s33, v6
	s_cmpk_gt_i32 s34, 0xfff
	s_nop 0
	v_addc_co_u32_e32 v7, vcc, 0, v7, vcc
	global_load_dword v156, v[14:15], off offset:2048
	global_load_dword v157, v[18:19], off offset:-4096
	global_load_dword v158, v[18:19], off
	global_load_dword v159, v[18:19], off offset:2048
	global_load_dword v160, v[22:23], off offset:-4096
	global_load_dword v161, v[22:23], off
	global_load_dword v162, v[22:23], off offset:2048
	global_load_dword v163, v[26:27], off offset:-4096
	global_load_dword v164, v[8:9], off offset:2048
	global_load_dword v165, v[12:13], off offset:2048
	global_load_dword v166, v[16:17], off offset:2048
	global_load_dword v167, v[20:21], off offset:2048
	global_load_dword v168, v[24:25], off offset:2048
	global_load_dword v169, v[28:29], off offset:2048
	global_load_dword v170, v[10:11], off offset:-4096
	global_load_dword v171, v[10:11], off
	global_load_dword v172, v[14:15], off
	global_load_dword v173, v[10:11], off offset:2048
	global_load_dword v174, v[14:15], off offset:-4096
	global_load_dword v175, v[32:33], off offset:2048
	global_load_dword v176, v[26:27], off
	global_load_dword v177, v[26:27], off offset:2048
	global_load_dword v178, v[30:31], off offset:-4096
	global_load_dword v179, v[30:31], off
	global_load_dword v180, v[30:31], off offset:2048
	global_load_dword v181, v[34:35], off offset:-4096
	global_load_dword v182, v[34:35], off
	global_load_dword v183, v[34:35], off offset:2048
	global_load_dword v184, v[6:7], off
	global_load_dword v185, v[6:7], off offset:2048
	v_lshl_add_u64 v[22:23], v[4:5], 0, s[4:5]
	s_cselect_b32 s47, 0, 1
.Lvt_nold:
	global_store_dwordx4 v[186:187], v[104:107], off
	global_store_dwordx4 v[186:187], v[108:111], off offset:512
	global_store_dwordx4 v[186:187], v[112:115], off offset:1024
	global_store_dwordx4 v[186:187], v[116:119], off offset:1536
	s_cmp_lg_u32 s48, 0
	s_cbranch_scc1 .Lvt_top
